# v57 plus group-0 row-sum chain in P.V gaps and second K/V tile DMA issued before the first barrier of each diff unit
# speedup vs baseline: 1.0213x; 1.0020x over previous
; __device__ __forceinline__ void diff_unit(const DiffArgs& A, int b, int h, int qb, char* lds, int wv) {
;     const int tid = opaque_tid(wv), wid = __builtin_amdgcn_readfirstlane(tid >> 6), lane = tid & 63, r32 = lane & 31, hi = lane >> 5, c = wid >> 2, wq = wid & 3;
;     const char* Pb = (const char*)A.proj + ((size_t)b * SEQ * INC + h * 128) * 2;
;     char* V_lds = lds; char* K_lds = lds + 4 * SHM_V;
;     float* wsl = (float*)(lds + 131072) + wid * 64;
;     int t_lo, nt; float nM2, lam, lam_init;
;     { int a_ = A.nM2b, b_ = A.lamb, c_ = A.laminitb;
;       asm volatile("" : "+s"(a_), "+s"(b_), "+s"(c_)); nM2 = __int_as_float(a_); lam = __int_as_float(b_); lam_init = __int_as_float(c_); }
;     const float slope = exp2f(-8.0f * (float)(h + 1) / 6.0f);
;     const float nslope2 = uni(-slope * LOG2E);
;     { const float Df = (151.0f + 2.0f * (-nM2)) / (-nslope2); const int Dk = Df > 20000.f ? 20000 : (int)Df + 1; const int i0 = qb * 128;
;       int lo_ = i0 - Dk + 1; lo_ = lo_ > 0 ? (lo_ >> 6) : 0; int hi_ = (i0 + 126 + Dk) >> 6; hi_ = hi_ > SEQ / KVBLK - 1 ? SEQ / KVBLK - 1 : hi_;
;     ...
;       t_lo = __builtin_amdgcn_readfirstlane(lo_); nt = __builtin_amdgcn_readfirstlane(hi_ - lo_ + 1); }
;     const int ipos = qb * 128 + wq * 32 + r32;
;     float l_reg = 0; f32x16 o[4] = {}; bf16x8 qr[4];
;     { const char* Qw = Pb + (size_t)(qb * 128 + wq * 32) * (INC * 2) + (C_DQ + c * 64) * 2; const unsigned qoff = (unsigned)((r32 * INC + hi * 8) * 2);
; #pragma unroll
;       for (int d0 = 0; d0 < 4; ++d0) qr[d0] = *reinterpret_cast<const bf16x8*>(Qw + qoff + d0 * 32); }
;     const int colB0 = c * 128;
;     const int krow = wid * 4 + (lane >> 4), kcc = (lane & 15) ^ (krow & 15);
;     const unsigned koff = (unsigned)((krow * INC + kcc * 8) * 2);
;     const int vkey = (wid >> 2) * 16 + (((wid >> 1) & 1) << 3) + (((lane >> 4) & 1) << 2) + ((lane >> 2) & 3)  , vcol = ((wid & 1) * 2 + (lane >> 5)) * 32 + (lane & 3) * 8;
;     const unsigned voff = (unsigned)((vkey * INC + vcol) * 2 + (C_DV - C_DK) * 2);
;     const int vb0 = (int)(uintptr_t)V_lds + v_rd_base(lane);
;     const char* Pk = Pb + (size_t)(t_lo * KVBLK) * (INC * 2) + C_DK * 2; int iposk = ipos - t_lo * KVBLK - 4 * hi; asm volatile("" : "+v"(iposk));     const int relw = t_lo * KVBLK - (qb * 128 + wq * 32);
;     typedef __attribute__((address_space(3))) unsigned lds_u32;
.LBB0_221:
	s_bfe_u32 s79, s20, 0x10006
	s_mul_i32 s6, s79, 0x3800000
	s_and_b32 s30, s20, 0xffffff80
	s_sub_i32 s6, s6, s30
	s_add_i32 s84, s6, 0x280
	s_ashr_i32 s17, s3, 6
	s_ashr_i32 s0, s3, 8
	s_lshl_b64 s[6:7], s[84:85], 1
	s_add_u32 s31, s80, s6
	s_addc_u32 s84, s81, s7
	s_lshl_b32 s23, s17, 5
	s_sub_i32 s62, s1, s8
	s_and_b32 s1, s23, 0x60
	s_or_b32 s9, s1, s9
	s_mul_i32 s6, s9, 0x3800
	s_add_u32 s6, s31, s6
	s_addc_u32 s7, s84, 0
	s_lshl_b32 s52, s0, 7
	v_and_b32_e32 v2, 31, v3
	v_bfe_u32 v5, v3, 5, 1
	s_ashr_i32 s18, s52, 31
	s_add_u32 s6, s6, s52
	v_lshlrev_b32_e32 v4, 4, v5
	v_mul_u32_u24_e32 v0, 0x3800, v2
	s_addc_u32 s7, s7, s18
	v_or_b32_e32 v176, v4, v0
	v_lshl_add_u64 v[0:1], s[6:7], 0, v[176:177]
	s_mov_b64 s[6:7], 0x1800
	v_lshl_add_u64 v[6:7], v[0:1], 0, s[6:7]
	s_movk_i32 s6, 0x1000
	v_add_co_u32_e32 v0, vcc, s6, v0
	s_lshl_b32 s6, s17, 2
	s_nop 0
	v_addc_co_u32_e32 v1, vcc, 0, v1, vcc
	global_load_dwordx4 v[168:171], v[6:7], off offset:32
	global_load_dwordx4 v[164:167], v[6:7], off offset:64
	global_load_dwordx4 v[172:175], v[0:1], off offset:2048
	global_load_dwordx4 v[160:163], v[6:7], off offset:96
	v_bfe_u32 v0, v3, 4, 2
	v_or_b32_e32 v1, s6, v0
	v_bitop3_b32 v0, s6, v3, v0 bitop3:0x36
	s_movk_i32 s18, 0x1c00
	v_mul_lo_u32 v1, v1, s18
	v_lshlrev_b32_e32 v0, 3, v0
	s_movk_i32 s6, 0x78
	v_and_or_b32 v0, v0, s6, v1
	s_lshr_b32 s7, s3, 4
	v_lshlrev_b32_e32 v176, 1, v0
	s_lshl_b32 s6, s0, 4
	s_and_b32 s7, s7, 8
	v_lshrrev_b32_e32 v0, 2, v3
	s_or_b32 s6, s6, s7
	v_and_b32_e32 v0, 4, v0
	v_bfe_u32 v1, v3, 2, 2
	v_or3_b32 v0, s6, v0, v1
	s_lshl_b32 s6, s17, 1
	v_and_or_b32 v1, s6, 2, v5
	s_lshl_b32 s6, s8, 6
	s_mul_i32 s7, s8, 0xe0000
	s_mul_hi_i32 s8, s6, 0x3800
	s_add_u32 s20, s31, s7
	v_lshlrev_b32_e32 v6, 3, v3
	s_addc_u32 s21, s84, s8
	v_lshlrev_b32_e32 v1, 5, v1
	v_and_b32_e32 v6, 24, v6
	v_mul_lo_u32 v0, v0, s18
	s_add_u32 s18, s20, 0x1e00
	v_or3_b32 v0, v1, v6, v0
	s_addc_u32 s19, s21, 0
	v_lshl_or_b32 v1, v5, 2, s6
	s_sub_i32 s63, s6, s9
	s_lshl_b32 s6, s17, 10
	s_add_i32 s24, s6, 0
	v_lshl_add_u32 v188, v0, 1, v234
	v_or_b32_e32 v0, s9, v2
	s_add_i32 s25, s24, 0x10000
	v_sub_u32_e32 v236, v0, v1
	s_mov_b32 m0, s25
	s_add_u32 s6, s20, 0x71e00
	global_load_lds_dwordx4 v176, s[18:19]
	s_addc_u32 s7, s21, 0
	s_add_i32 m0, s24, 0x12000
	v_cvt_f32_i32_e32 v0, v236
	global_load_lds_dwordx4 v176, s[6:7]
	s_mov_b32 m0, s24
	s_nop 0
	global_load_lds_dwordx4 v188, s[18:19]
	s_add_i32 m0, s24, 0x2000
	s_nop 0
	global_load_lds_dwordx4 v188, s[6:7]
	s_add_u32 s6, s20, 0xe1e00
	s_addc_u32 s7, s21, 0
	s_add_i32 m0, s24, 0x14000
	s_add_u32 s8, s20, 0x151e00
	global_load_lds_dwordx4 v176, s[6:7]
	s_addc_u32 s9, s21, 0
	s_add_i32 m0, s24, 0x16000
	s_nop 0
	global_load_lds_dwordx4 v176, s[8:9]
	s_add_i32 m0, s24, 0x4000
	s_nop 0
	global_load_lds_dwordx4 v188, s[6:7]
	s_add_i32 m0, s24, 0x6000
	s_sub_i32 s6, s63, 31
	global_load_lds_dwordx4 v188, s[8:9]
	s_waitcnt vmcnt(0)
	s_waitcnt vmcnt(0) lgkmcnt(0)
	s_barrier
	s_cmp_lt_u32 s6, 0xffffffa3
	s_mov_b64 s[6:7], -1
	s_cbranch_scc1 .LBB0_223
	v_add_f32_e32 v1, -1.0, v0
	v_pk_add_f32 v[6:7], v[0:1], s[26:27] op_sel_hi:[1,0]
	s_mov_b32 s6, -2.0
	v_and_b32_e32 v7, 0x7fffffff, v7
	v_and_b32_e32 v6, 0x7fffffff, v6
	s_mov_b32 s7, 0xc0400000
	v_pk_fma_f32 v[64:65], v[6:7], v[186:187], s[16:17] op_sel_hi:[1,0,0]
	v_pk_add_f32 v[6:7], v[0:1], s[6:7] op_sel_hi:[0,1]
	v_pk_add_f32 v[8:9], v[6:7], s[26:27] op_sel_hi:[1,0]
	s_mov_b32 s6, 0xc1000000
	v_and_b32_e32 v9, 0x7fffffff, v9
	v_and_b32_e32 v8, 0x7fffffff, v8
	s_mov_b32 s7, 0xc1100000
	v_pk_fma_f32 v[66:67], v[8:9], v[186:187], s[16:17] op_sel_hi:[1,0,0]
	v_pk_add_f32 v[8:9], v[0:1], s[6:7] op_sel_hi:[0,1]
	v_pk_add_f32 v[10:11], v[8:9], s[26:27] op_sel_hi:[1,0]
	s_mov_b32 s6, 0xc1200000
	v_and_b32_e32 v11, 0x7fffffff, v11
	v_and_b32_e32 v10, 0x7fffffff, v10
	s_mov_b32 s7, 0xc1300000
	v_pk_fma_f32 v[68:69], v[10:11], v[186:187], s[16:17] op_sel_hi:[1,0,0]
	v_pk_add_f32 v[10:11], v[0:1], s[6:7] op_sel_hi:[0,1]
	v_pk_add_f32 v[12:13], v[10:11], s[26:27] op_sel_hi:[1,0]
	s_mov_b32 s6, 0xc1800000
	v_and_b32_e32 v13, 0x7fffffff, v13
	v_and_b32_e32 v12, 0x7fffffff, v12
	s_mov_b32 s7, 0xc1880000
	v_pk_fma_f32 v[70:71], v[12:13], v[186:187], s[16:17] op_sel_hi:[1,0,0]
	v_pk_add_f32 v[12:13], v[0:1], s[6:7] op_sel_hi:[0,1]
	v_pk_add_f32 v[14:15], v[12:13], s[26:27] op_sel_hi:[1,0]
	s_mov_b32 s6, 0xc1900000
	v_and_b32_e32 v15, 0x7fffffff, v15
	v_and_b32_e32 v14, 0x7fffffff, v14
	s_mov_b32 s7, 0xc1980000
	v_pk_fma_f32 v[72:73], v[14:15], v[186:187], s[16:17] op_sel_hi:[1,0,0]
	v_pk_add_f32 v[14:15], v[0:1], s[6:7] op_sel_hi:[0,1]
	v_pk_add_f32 v[16:17], v[14:15], s[26:27] op_sel_hi:[1,0]
	s_mov_b32 s6, 0xc1c00000
	v_and_b32_e32 v17, 0x7fffffff, v17
	v_and_b32_e32 v16, 0x7fffffff, v16
	s_mov_b32 s7, 0xc1c80000
	v_pk_fma_f32 v[74:75], v[16:17], v[186:187], s[16:17] op_sel_hi:[1,0,0]
	v_pk_add_f32 v[16:17], v[0:1], s[6:7] op_sel_hi:[0,1]
	v_pk_add_f32 v[18:19], v[16:17], s[26:27] op_sel_hi:[1,0]
	s_mov_b32 s6, 0xc1d00000
	v_and_b32_e32 v19, 0x7fffffff, v19
	v_and_b32_e32 v18, 0x7fffffff, v18
	s_mov_b32 s7, 0xc1d80000
	v_pk_fma_f32 v[76:77], v[18:19], v[186:187], s[16:17] op_sel_hi:[1,0,0]
	v_pk_add_f32 v[18:19], v[0:1], s[6:7] op_sel_hi:[0,1]
	v_add_f32_e32 v5, 0xc2000000, v18
	v_and_b32_e32 v7, 0x7fffffff, v7
	v_and_b32_e32 v6, 0x7fffffff, v6
	v_and_b32_e32 v9, 0x7fffffff, v9
	v_and_b32_e32 v8, 0x7fffffff, v8
	v_and_b32_e32 v11, 0x7fffffff, v11
	v_and_b32_e32 v10, 0x7fffffff, v10
	v_and_b32_e32 v13, 0x7fffffff, v13
	v_and_b32_e32 v12, 0x7fffffff, v12
	v_and_b32_e32 v15, 0x7fffffff, v15
	v_and_b32_e32 v14, 0x7fffffff, v14
	v_and_b32_e32 v17, 0x7fffffff, v17
	v_and_b32_e32 v16, 0x7fffffff, v16
	v_and_b32_e32 v21, 0x7fffffff, v19
	v_and_b32_e32 v20, 0x7fffffff, v18
	v_and_b32_e32 v22, 0x7fffffff, v0
	v_and_b32_e32 v23, 0x7fffffff, v1
	v_add_f32_e32 v1, 0xc2000000, v19
	v_fma_f32 v78, |v5|, v186, s16
	v_pk_fma_f32 v[94:95], v[20:21], v[186:187], s[16:17] op_sel_hi:[1,0,0]
	v_pk_fma_f32 v[92:93], v[16:17], v[186:187], s[16:17] op_sel_hi:[1,0,0]
	v_pk_fma_f32 v[90:91], v[14:15], v[186:187], s[16:17] op_sel_hi:[1,0,0]
	v_pk_fma_f32 v[88:89], v[12:13], v[186:187], s[16:17] op_sel_hi:[1,0,0]
	v_pk_fma_f32 v[86:87], v[10:11], v[186:187], s[16:17] op_sel_hi:[1,0,0]
	v_pk_fma_f32 v[84:85], v[8:9], v[186:187], s[16:17] op_sel_hi:[1,0,0]
	v_pk_fma_f32 v[82:83], v[6:7], v[186:187], s[16:17] op_sel_hi:[1,0,0]
	v_pk_fma_f32 v[80:81], v[22:23], v[186:187], s[16:17] op_sel_hi:[1,0,0]
	v_fma_f32 v79, |v1|, v186, s16
	s_mov_b64 s[6:7], 0

; #define SBAR() __builtin_amdgcn_sched_barrier(0)
; #define PK4(P, BASE, OUT) do { u32x4 w = {cvtpk(P[BASE + 0], P[BASE + 1]), cvtpk(P[BASE + 2], P[BASE + 3]), cvtpk(P[BASE + 4], P[BASE + 5]), cvtpk(P[BASE + 6], P[BASE + 7])}; \
;     OUT = *reinterpret_cast<bf16x8*>(&w); } while (0)
; #define STAGE(t) do { const char* kt_ = Pk + (size_t)((t) * KVBLK) * (INC * 2); const int so_ = ((t) & 3) * SHM_K; \
;     GLDS(kt_ + koff, ldsA + 4 * SHM_V + so_); GLDS(kt_ + 32 * INC * 2 + koff, ldsA + 4 * SHM_V + so_ + 8192); \
;     GLDS(kt_ + voff, ldsA + so_); GLDS(kt_ + 32 * INC * 2 + voff, ldsA + so_ + 8192); } while (0)
; #define BIAS(P0, P1, t) bias_init(P0, P1, (float)(iposk - (t) * KVBLK), nslope2, nM2, relw + (t) * KVBLK)
; __device__ __forceinline__ void pack_p(const f32x16& p0, const f32x16& p1, float& l_reg, bf16x8& pa0, bf16x8& pa1, bf16x8& pa2, bf16x8& pa3) {
;     float ps = 0;
; #pragma unroll
;     for (int r = 0; r < 16; ++r) ps += p0[r];
; #pragma unroll
;     for (int r = 0; r < 16; ++r) ps += p1[r];
;     l_reg += ps;
;     ...
;     PK4(p0, 0, pa0); PK4(p0, 8, pa1); PK4(p1, 0, pa2); PK4(p1, 8, pa3);
;     ...
; }
; template <int ND0> __device__ __forceinline__ void qkt(f32x16& p0, f32x16& p1, const char* Ks, const bf16x8* qr, int r32, int hi, int colB0) {
; #pragma unroll
;     for (int d0 = 0; d0 < ND0; ++d0) { const int cb = colB0 + (d0 * 16 + hi * 8) * 2;
;         const bf16x8 b0 = *reinterpret_cast<const bf16x8*>(Ks + KSWZ(r32, cb));
;         const bf16x8 b1 = *reinterpret_cast<const bf16x8*>(Ks + KSWZ(32 + r32, cb));
;         p0 = __builtin_amdgcn_mfma_f32_32x32x16_bf16(b0, qr[d0], p0, 0, 0, 0);
;         p1 = __builtin_amdgcn_mfma_f32_32x32x16_bf16(b1, qr[d0], p1, 0, 0, 0); }
; }
; __device__ __forceinline__ void diff_unit(const DiffArgs& A, int b, int h, int qb, char* lds, int wv) {
;     ...
;             STAGE(j + 1);
;             SBAR(); BIAS(pB0, pB1, j); qkt<4>(pB0, pB1, K_lds + SLOT(j), qr, r32p, hip, colB0);
;             exp_half(pA1); pack_p(pA0, pA1, l_reg, pa0, pa1, pa2, pa3); SBAR();
.LBB0_247:
	v_exp_f32_e32 v195, v100
	v_exp_f32_e32 v100, v106
	s_add_i32 s55, s55, 0
	s_add_i32 s55, s55, 0x10000
	v_exp_f32_e32 v202, v101
	v_exp_f32_e32 v101, v107
	v_add_u32_e32 v107, s55, v131
	v_exp_f32_e32 v187, v97
	v_exp_f32_e32 v194, v99
	v_exp_f32_e32 v203, v102
	v_exp_f32_e32 v204, v103
	v_exp_f32_e32 v97, v104
	v_exp_f32_e32 v99, v105
	v_exp_f32_e32 v102, v108
	v_exp_f32_e32 v103, v109
	v_exp_f32_e32 v104, v110
	v_exp_f32_e32 v105, v111
	ds_read_b128 v[108:111], v107
	ds_read_b128 v[140:143], v107 offset:8192
	s_waitcnt lgkmcnt(0)
	v_mfma_f32_32x32x16_bf16 v[112:127], v[108:111], v[172:175], v[112:127]
	v_add_u32_e32 v107, s55, v133
	v_exp_f32_e32 v96, v96
	v_exp_f32_e32 v98, v98
	v_exp_f32_e32 v129, v85
	v_exp_f32_e32 v130, v86
	v_mfma_f32_32x32x16_bf16 v[64:79], v[140:143], v[172:175], v[64:79]
	ds_read_b128 v[108:111], v107
	ds_read_b128 v[140:143], v107 offset:8192
	v_add_u32_e32 v107, s55, v135
	v_exp_f32_e32 v132, v87
	v_exp_f32_e32 v134, v88
	s_waitcnt lgkmcnt(0)
	v_mfma_f32_32x32x16_bf16 v[112:127], v[108:111], v[168:171], v[112:127]
	v_exp_f32_e32 v136, v89
	v_exp_f32_e32 v138, v90
	v_mfma_f32_32x32x16_bf16 v[64:79], v[140:143], v[168:171], v[64:79]
	ds_read_b128 v[108:111], v107
	ds_read_b128 v[140:143], v107 offset:8192
	v_add_u32_e32 v107, s55, v137
	v_exp_f32_e32 v95, v95
	s_waitcnt lgkmcnt(0)
	v_mfma_f32_32x32x16_bf16 v[112:127], v[108:111], v[164:167], v[112:127]
	s_add_i32 s52, s52, 2
	v_cvt_pk_bf16_f32 v85, v100, v101
	v_cvt_pk_bf16_f32 v86, v102, v103
	v_cvt_pk_bf16_f32 v87, v104, v105
	v_mfma_f32_32x32x16_bf16 v[64:79], v[140:143], v[164:167], v[64:79]
	ds_read_b128 v[108:111], v107
	ds_read_b128 v[140:143], v107 offset:8192
	v_exp_f32_e32 v107, v80
	v_add_f32_e32 v80, 0, v96
	v_add_f32_e32 v80, v187, v80
	v_add_f32_e32 v80, v98, v80
	v_add_f32_e32 v80, v194, v80
	v_add_f32_e32 v80, v195, v80
	v_add_f32_e32 v80, v202, v80
	v_add_f32_e32 v80, v203, v80
	v_add_f32_e32 v80, v204, v80
	v_add_f32_e32 v80, v97, v80
	v_add_f32_e32 v80, v99, v80
	v_add_f32_e32 v80, v100, v80
	v_add_f32_e32 v80, v101, v80
	v_add_f32_e32 v80, v102, v80
	s_waitcnt lgkmcnt(0)
	v_mfma_f32_32x32x16_bf16 v[112:127], v[108:111], v[160:163], v[112:127]
	v_exp_f32_e32 v108, v81
	v_add_f32_e32 v80, v103, v80
	v_exp_f32_e32 v109, v82
	v_add_f32_e32 v80, v104, v80
	v_exp_f32_e32 v110, v83
	v_add_f32_e32 v80, v105, v80
	v_exp_f32_e32 v111, v84
	v_add_f32_e32 v80, v107, v80
	v_add_f32_e32 v80, v108, v80
	v_add_f32_e32 v80, v109, v80
	v_add_f32_e32 v80, v110, v80
	v_add_f32_e32 v80, v111, v80
	v_add_f32_e32 v80, v129, v80
	v_add_f32_e32 v80, v130, v80
	v_mfma_f32_32x32x16_bf16 v[64:79], v[140:143], v[160:163], v[64:79]
	v_exp_f32_e32 v140, v91
	v_add_f32_e32 v80, v132, v80
	v_exp_f32_e32 v141, v92
	v_add_f32_e32 v80, v134, v80
	v_exp_f32_e32 v142, v93
	v_add_f32_e32 v80, v136, v80
	v_exp_f32_e32 v143, v94
	v_add_f32_e32 v80, v138, v80
	v_add_f32_e32 v80, v140, v80
	v_add_f32_e32 v80, v141, v80
	v_add_f32_e32 v80, v142, v80
	v_add_f32_e32 v80, v143, v80
	v_add_f32_e32 v80, v95, v80
	v_add_f32_e32 v128, v222, v80
	v_cvt_pk_bf16_f32 v80, v96, v187
	v_cvt_pk_bf16_f32 v81, v98, v194
	v_cvt_pk_bf16_f32 v82, v195, v202
	v_cvt_pk_bf16_f32 v83, v203, v204
	v_cvt_pk_bf16_f32 v84, v97, v99
	v_cvt_pk_bf16_f32 v88, v107, v108
	v_cvt_pk_bf16_f32 v89, v109, v110
	v_cvt_pk_bf16_f32 v90, v111, v129
	v_cvt_pk_bf16_f32 v91, v130, v132
	v_cvt_pk_bf16_f32 v92, v134, v136
	v_cvt_pk_bf16_f32 v93, v138, v140
	v_cvt_pk_bf16_f32 v94, v141, v142
	v_cvt_pk_bf16_f32 v95, v143, v95
	v_add_u32_e32 v129, s56, v252
	s_setprio 1
	ds_read_b64_tr_b16 v[96:97], v129 offset:0
	ds_read_b64_tr_b16 v[98:99], v129 offset:0x800
	ds_read_b64_tr_b16 v[100:101], v129 offset:0x200
	ds_read_b64_tr_b16 v[102:103], v129 offset:0xa00
	ds_read_b64_tr_b16 v[104:105], v129 offset:0x400
	ds_read_b64_tr_b16 v[106:107], v129 offset:0xc00
	ds_read_b64_tr_b16 v[108:109], v129 offset:0x600
	ds_read_b64_tr_b16 v[110:111], v129 offset:0xe00
	s_waitcnt lgkmcnt(6)
; #define SBAR() __builtin_amdgcn_sched_barrier(0)
; #define ENDI() do { asm volatile("s_waitcnt vmcnt(0)" ::: "memory"); __syncthreads(); } while (0)
; template <int KS> __device__ __forceinline__ void pv_ks(f32x16* o, int vb, bf16x8 pa) {
;     const s16x4 l0 = tr_read<v_rd_off(0, KS, 0)>(vb), h0 = tr_read<v_rd_off(0, KS, 1)>(vb), l1 = tr_read<v_rd_off(1, KS, 0)>(vb), h1 = tr_read<v_rd_off(1, KS, 1)>(vb);
;     const s16x4 l2 = tr_read<v_rd_off(2, KS, 0)>(vb), h2 = tr_read<v_rd_off(2, KS, 1)>(vb), l3 = tr_read<v_rd_off(3, KS, 0)>(vb), h3 = tr_read<v_rd_off(3, KS, 1)>(vb);
;     ...
;     asm volatile("s_waitcnt lgkmcnt(6)" ::: "memory"); SBAR();
;     o[0] = __builtin_amdgcn_mfma_f32_32x32x16_bf16(pa, PK(l0, h0), o[0], 0, 0, 0);
;     asm volatile("s_waitcnt lgkmcnt(4)" ::: "memory"); SBAR();
;     o[1] = __builtin_amdgcn_mfma_f32_32x32x16_bf16(pa, PK(l1, h1), o[1], 0, 0, 0);
;     asm volatile("s_waitcnt lgkmcnt(2)" ::: "memory"); SBAR();
;     o[2] = __builtin_amdgcn_mfma_f32_32x32x16_bf16(pa, PK(l2, h2), o[2], 0, 0, 0);
;     asm volatile("s_waitcnt lgkmcnt(0)" ::: "memory"); SBAR();
;     o[3] = __builtin_amdgcn_mfma_f32_32x32x16_bf16(pa, PK(l3, h3), o[3], 0, 0, 0);
;     ...
; }
; __device__ __forceinline__ void pv_d0(f32x16* o, int vb, bf16x8 pa0, bf16x8 pa1, bf16x8 pa2, bf16x8 pa3) {
;     __builtin_amdgcn_s_setprio(1);
;     pv_ks<0>(o, vb, pa0); pv_ks<1>(o, vb, pa1); pv_ks<2>(o, vb, pa2); pv_ks<3>(o, vb, pa3);
;     __builtin_amdgcn_s_setprio(0);
; }
; __device__ __forceinline__ void exp_half(f32x16& p) {
; #pragma unroll
;     for (int r = 0; r < 16; ++r) p[r] = __builtin_amdgcn_exp2f(p[r]);
; }
; __device__ __forceinline__ void diff_unit(const DiffArgs& A, int b, int h, int qb, char* lds, int wv) {
;     ...
;             pv_d0(o, vb0 + SLOT(j - 1), pa0, pa1, pa2, pa3); exp_half(pB0);
;             ENDI();
	v_mfma_f32_32x32x16_bf16 v[48:63], v[80:83], v[96:99], v[48:63]
	ds_read_b64_tr_b16 v[96:97], v129 offset:0x1000
	ds_read_b64_tr_b16 v[98:99], v129 offset:0x1800
	v_exp_f32_e32 v132, v113
	s_waitcnt lgkmcnt(6)
	v_mfma_f32_32x32x16_bf16 v[32:47], v[80:83], v[100:103], v[32:47]
	ds_read_b64_tr_b16 v[100:101], v129 offset:0x1200
	ds_read_b64_tr_b16 v[102:103], v129 offset:0x1a00
	v_exp_f32_e32 v140, v114
	s_waitcnt lgkmcnt(6)
	v_mfma_f32_32x32x16_bf16 v[16:31], v[80:83], v[104:107], v[16:31]
	ds_read_b64_tr_b16 v[104:105], v129 offset:0x1400
	ds_read_b64_tr_b16 v[106:107], v129 offset:0x1c00
	v_exp_f32_e32 v138, v115
	s_waitcnt lgkmcnt(6)
	v_mfma_f32_32x32x16_bf16 v[0:15], v[80:83], v[108:111], v[0:15]
	ds_read_b64_tr_b16 v[108:109], v129 offset:0x1600
	ds_read_b64_tr_b16 v[110:111], v129 offset:0x1e00
	v_exp_f32_e32 v148, v116
	s_waitcnt lgkmcnt(6)
	v_mfma_f32_32x32x16_bf16 v[48:63], v[84:87], v[96:99], v[48:63]
	ds_read_b64_tr_b16 v[96:97], v129 offset:0x2000
	ds_read_b64_tr_b16 v[98:99], v129 offset:0x2800
	v_exp_f32_e32 v146, v117
	s_waitcnt lgkmcnt(6)
	v_mfma_f32_32x32x16_bf16 v[32:47], v[84:87], v[100:103], v[32:47]
	ds_read_b64_tr_b16 v[100:101], v129 offset:0x2200
	ds_read_b64_tr_b16 v[102:103], v129 offset:0x2a00
	v_exp_f32_e32 v156, v118
	s_waitcnt lgkmcnt(6)
	v_mfma_f32_32x32x16_bf16 v[16:31], v[84:87], v[104:107], v[16:31]
	ds_read_b64_tr_b16 v[104:105], v129 offset:0x2400
	ds_read_b64_tr_b16 v[106:107], v129 offset:0x2c00
	v_exp_f32_e32 v154, v119
	s_waitcnt lgkmcnt(6)
	v_mfma_f32_32x32x16_bf16 v[0:15], v[84:87], v[108:111], v[0:15]
	ds_read_b64_tr_b16 v[108:109], v129 offset:0x2600
	ds_read_b64_tr_b16 v[110:111], v129 offset:0x2e00
	v_exp_f32_e32 v158, v120
	s_waitcnt lgkmcnt(6)
	v_mfma_f32_32x32x16_bf16 v[48:63], v[88:91], v[96:99], v[48:63]
	ds_read_b64_tr_b16 v[96:97], v129 offset:0x3000
	ds_read_b64_tr_b16 v[98:99], v129 offset:0x3800
	v_exp_f32_e32 v130, v121
	s_waitcnt lgkmcnt(6)
	v_mfma_f32_32x32x16_bf16 v[32:47], v[88:91], v[100:103], v[32:47]
	ds_read_b64_tr_b16 v[100:101], v129 offset:0x3200
	ds_read_b64_tr_b16 v[102:103], v129 offset:0x3a00
	v_exp_f32_e32 v136, v122
	s_waitcnt lgkmcnt(6)
	v_mfma_f32_32x32x16_bf16 v[16:31], v[88:91], v[104:107], v[16:31]
	ds_read_b64_tr_b16 v[104:105], v129 offset:0x3400
	ds_read_b64_tr_b16 v[106:107], v129 offset:0x3c00
	v_exp_f32_e32 v134, v123
	s_waitcnt lgkmcnt(6)
	v_mfma_f32_32x32x16_bf16 v[0:15], v[88:91], v[108:111], v[0:15]
	ds_read_b64_tr_b16 v[108:109], v129 offset:0x3600
	ds_read_b64_tr_b16 v[110:111], v129 offset:0x3e00
	v_exp_f32_e32 v144, v124
	s_waitcnt lgkmcnt(6)
	v_mfma_f32_32x32x16_bf16 v[48:63], v[92:95], v[96:99], v[48:63]
	v_exp_f32_e32 v142, v125
	s_waitcnt lgkmcnt(4)
	v_mfma_f32_32x32x16_bf16 v[32:47], v[92:95], v[100:103], v[32:47]
	v_exp_f32_e32 v152, v126
	s_waitcnt lgkmcnt(2)
	v_mfma_f32_32x32x16_bf16 v[16:31], v[92:95], v[104:107], v[16:31]
	v_exp_f32_e32 v150, v127
	s_waitcnt lgkmcnt(0)
	v_mfma_f32_32x32x16_bf16 v[0:15], v[92:95], v[108:111], v[0:15]
	v_exp_f32_e32 v129, v112
	s_setprio 0
	s_waitcnt vmcnt(0)
	s_add_i32 s53, s53, 0x8000
	s_addk_i32 s54, 0x80
	s_cmp_ge_i32 s52, s62
	v_add_u32_e32 v139, 0xffffff80, v139
	s_waitcnt vmcnt(0)
	s_barrier
	s_cbranch_scc1 .LBB0_257

; template <int KS> __device__ __forceinline__ void pv_ks(f32x16* o, int vb, bf16x8 pa) {
;     const s16x4 l0 = tr_read<v_rd_off(0, KS, 0)>(vb), h0 = tr_read<v_rd_off(0, KS, 1)>(vb), l1 = tr_read<v_rd_off(1, KS, 0)>(vb), h1 = tr_read<v_rd_off(1, KS, 1)>(vb);
;     const s16x4 l2 = tr_read<v_rd_off(2, KS, 0)>(vb), h2 = tr_read<v_rd_off(2, KS, 1)>(vb), l3 = tr_read<v_rd_off(3, KS, 0)>(vb), h3 = tr_read<v_rd_off(3, KS, 1)>(vb);
;     ...
;     asm volatile("s_waitcnt lgkmcnt(6)" ::: "memory"); SBAR();
;     o[0] = __builtin_amdgcn_mfma_f32_32x32x16_bf16(pa, PK(l0, h0), o[0], 0, 0, 0);
;     asm volatile("s_waitcnt lgkmcnt(4)" ::: "memory"); SBAR();
;     o[1] = __builtin_amdgcn_mfma_f32_32x32x16_bf16(pa, PK(l1, h1), o[1], 0, 0, 0);
;     asm volatile("s_waitcnt lgkmcnt(2)" ::: "memory"); SBAR();
;     o[2] = __builtin_amdgcn_mfma_f32_32x32x16_bf16(pa, PK(l2, h2), o[2], 0, 0, 0);
;     asm volatile("s_waitcnt lgkmcnt(0)" ::: "memory"); SBAR();
;     o[3] = __builtin_amdgcn_mfma_f32_32x32x16_bf16(pa, PK(l3, h3), o[3], 0, 0, 0);
;     ...
; }
; __device__ __forceinline__ void pv_d0(f32x16* o, int vb, bf16x8 pa0, bf16x8 pa1, bf16x8 pa2, bf16x8 pa3) {
;     __builtin_amdgcn_s_setprio(1);
;     pv_ks<0>(o, vb, pa0); pv_ks<1>(o, vb, pa1); pv_ks<2>(o, vb, pa2); pv_ks<3>(o, vb, pa3);
;     __builtin_amdgcn_s_setprio(0);
; }
; __device__ __forceinline__ void exp_half(f32x16& p) {
; #pragma unroll
;     for (int r = 0; r < 16; ++r) p[r] = __builtin_amdgcn_exp2f(p[r]);
; }
; __device__ __forceinline__ void pack_p(const f32x16& p0, const f32x16& p1, float& l_reg, bf16x8& pa0, bf16x8& pa1, bf16x8& pa2, bf16x8& pa3) {
;     float ps = 0;
; #pragma unroll
;     for (int r = 0; r < 16; ++r) ps += p0[r];
; #pragma unroll
;     for (int r = 0; r < 16; ++r) ps += p1[r];
;     l_reg += ps;
;     ...
;     PK4(p0, 0, pa0); PK4(p0, 8, pa1); PK4(p1, 0, pa2); PK4(p1, 8, pa3);
;     ...
; }
; template <int ND0> __device__ __forceinline__ void qkt(f32x16& p0, f32x16& p1, const char* Ks, const bf16x8* qr, int r32, int hi, int colB0) {
; #pragma unroll
;     for (int d0 = 0; d0 < ND0; ++d0) { const int cb = colB0 + (d0 * 16 + hi * 8) * 2;
;         const bf16x8 b0 = *reinterpret_cast<const bf16x8*>(Ks + KSWZ(r32, cb));
;         const bf16x8 b1 = *reinterpret_cast<const bf16x8*>(Ks + KSWZ(32 + r32, cb));
;         p0 = __builtin_amdgcn_mfma_f32_32x32x16_bf16(b0, qr[d0], p0, 0, 0, 0);
.LBB0_252:
	s_add_i32 s56, s53, 0xffff4000
	s_and_b32 s56, s56, 0xc000
	s_add_i32 s58, s56, 0
	s_add_i32 s58, s58, 0x10000
	v_add_u32_e32 v116, s58, v131
	ds_read_b128 v[112:115], v116
	ds_read_b128 v[116:119], v116 offset:8192
	v_exp_f32_e32 v141, v64
	v_exp_f32_e32 v143, v65
	v_exp_f32_e32 v145, v66
	s_waitcnt lgkmcnt(0)
	v_mfma_f32_32x32x16_bf16 v[96:111], v[112:115], v[172:175], v[96:111]
	v_exp_f32_e32 v147, v67
	v_exp_f32_e32 v149, v68
	v_exp_f32_e32 v151, v69
	v_exp_f32_e32 v153, v70
	v_exp_f32_e32 v155, v71
	v_exp_f32_e32 v157, v72
	v_exp_f32_e32 v159, v73
	v_mfma_f32_32x32x16_bf16 v[80:95], v[116:119], v[172:175], v[80:95]
	v_add_u32_e32 v116, s58, v133
	ds_read_b128 v[112:115], v116
	ds_read_b128 v[116:119], v116 offset:8192
	v_exp_f32_e32 v196, v74
	v_exp_f32_e32 v197, v75
	v_exp_f32_e32 v198, v76
	v_exp_f32_e32 v199, v77
	v_exp_f32_e32 v200, v78
	s_waitcnt lgkmcnt(0)
	v_mfma_f32_32x32x16_bf16 v[96:111], v[112:115], v[168:171], v[96:111]
	v_exp_f32_e32 v201, v79
	v_cvt_pk_bf16_f32 v64, v129, v132
	v_cvt_pk_bf16_f32 v65, v140, v138
	v_cvt_pk_bf16_f32 v66, v148, v146
	v_cvt_pk_bf16_f32 v67, v156, v154
	v_cvt_pk_bf16_f32 v68, v158, v130
	v_cvt_pk_bf16_f32 v69, v136, v134
	v_mfma_f32_32x32x16_bf16 v[80:95], v[116:119], v[168:171], v[80:95]
	v_add_u32_e32 v116, s58, v135
	ds_read_b128 v[112:115], v116
	ds_read_b128 v[116:119], v116 offset:8192
	v_cvt_pk_bf16_f32 v70, v144, v142
	v_cvt_pk_bf16_f32 v71, v152, v150
	v_cvt_pk_bf16_f32 v72, v141, v143
	v_cvt_pk_bf16_f32 v73, v145, v147
	v_cvt_pk_bf16_f32 v74, v149, v151
	s_waitcnt lgkmcnt(0)
	v_mfma_f32_32x32x16_bf16 v[96:111], v[112:115], v[164:167], v[96:111]
	v_cvt_pk_bf16_f32 v75, v153, v155
	v_cvt_pk_bf16_f32 v76, v157, v159
	v_cvt_pk_bf16_f32 v77, v196, v197
	v_cvt_pk_bf16_f32 v78, v198, v199
	v_cvt_pk_bf16_f32 v79, v200, v201
	v_mfma_f32_32x32x16_bf16 v[80:95], v[116:119], v[164:167], v[80:95]
	v_add_u32_e32 v116, s58, v137
	ds_read_b128 v[112:115], v116
	ds_read_b128 v[116:119], v116 offset:8192
	s_waitcnt lgkmcnt(0)
	v_mfma_f32_32x32x16_bf16 v[96:111], v[112:115], v[160:163], v[96:111]
	v_mfma_f32_32x32x16_bf16 v[80:95], v[116:119], v[160:163], v[80:95]
	s_and_b32 s58, s53, 0xc000
	v_add_u32_e32 v178, s58, v252
	s_setprio 1
	ds_read_b64_tr_b16 v[112:113], v178 offset:0
	ds_read_b64_tr_b16 v[114:115], v178 offset:0x800
	ds_read_b64_tr_b16 v[116:117], v178 offset:0x200
	ds_read_b64_tr_b16 v[118:119], v178 offset:0xa00
	ds_read_b64_tr_b16 v[120:121], v178 offset:0x400
	ds_read_b64_tr_b16 v[122:123], v178 offset:0xc00
	ds_read_b64_tr_b16 v[124:125], v178 offset:0x600
	ds_read_b64_tr_b16 v[126:127], v178 offset:0xe00
	s_waitcnt lgkmcnt(6)
	v_mfma_f32_32x32x16_bf16 v[48:63], v[64:67], v[112:115], v[48:63]
	ds_read_b64_tr_b16 v[112:113], v178 offset:0x1000
	ds_read_b64_tr_b16 v[114:115], v178 offset:0x1800
	v_add_f32_e32 v222, 0, v129
	v_add_f32_e32 v222, v132, v222
	s_waitcnt lgkmcnt(6)
	v_mfma_f32_32x32x16_bf16 v[32:47], v[64:67], v[116:119], v[32:47]
	ds_read_b64_tr_b16 v[116:117], v178 offset:0x1200
	ds_read_b64_tr_b16 v[118:119], v178 offset:0x1a00
	v_add_f32_e32 v222, v140, v222
	v_add_f32_e32 v222, v138, v222
	s_waitcnt lgkmcnt(6)
	v_mfma_f32_32x32x16_bf16 v[16:31], v[64:67], v[120:123], v[16:31]
	ds_read_b64_tr_b16 v[120:121], v178 offset:0x1400
	ds_read_b64_tr_b16 v[122:123], v178 offset:0x1c00
	v_add_f32_e32 v222, v148, v222
	v_add_f32_e32 v222, v146, v222
	s_waitcnt lgkmcnt(6)
	v_mfma_f32_32x32x16_bf16 v[0:15], v[64:67], v[124:127], v[0:15]
	ds_read_b64_tr_b16 v[124:125], v178 offset:0x1600
	ds_read_b64_tr_b16 v[126:127], v178 offset:0x1e00
	v_add_f32_e32 v222, v156, v222
	v_add_f32_e32 v222, v154, v222
	s_waitcnt lgkmcnt(6)
	v_mfma_f32_32x32x16_bf16 v[48:63], v[68:71], v[112:115], v[48:63]
	ds_read_b64_tr_b16 v[112:113], v178 offset:0x2000
	ds_read_b64_tr_b16 v[114:115], v178 offset:0x2800
	v_add_f32_e32 v222, v158, v222
	v_add_f32_e32 v222, v130, v222
	s_waitcnt lgkmcnt(6)
	v_mfma_f32_32x32x16_bf16 v[32:47], v[68:71], v[116:119], v[32:47]
	ds_read_b64_tr_b16 v[116:117], v178 offset:0x2200
	ds_read_b64_tr_b16 v[118:119], v178 offset:0x2a00
	v_add_f32_e32 v222, v136, v222
	v_add_f32_e32 v222, v134, v222
	s_waitcnt lgkmcnt(6)
	v_mfma_f32_32x32x16_bf16 v[16:31], v[68:71], v[120:123], v[16:31]
	ds_read_b64_tr_b16 v[120:121], v178 offset:0x2400
	ds_read_b64_tr_b16 v[122:123], v178 offset:0x2c00
	v_add_f32_e32 v222, v144, v222
	v_add_f32_e32 v222, v142, v222
	s_waitcnt lgkmcnt(6)
	v_mfma_f32_32x32x16_bf16 v[0:15], v[68:71], v[124:127], v[0:15]
	ds_read_b64_tr_b16 v[124:125], v178 offset:0x2600
	ds_read_b64_tr_b16 v[126:127], v178 offset:0x2e00
	v_add_f32_e32 v222, v152, v222
	v_add_f32_e32 v222, v150, v222
	s_waitcnt lgkmcnt(6)
	v_mfma_f32_32x32x16_bf16 v[48:63], v[72:75], v[112:115], v[48:63]
	ds_read_b64_tr_b16 v[112:113], v178 offset:0x3000
	ds_read_b64_tr_b16 v[114:115], v178 offset:0x3800
	v_add_f32_e32 v222, v141, v222
	v_add_f32_e32 v222, v143, v222
	s_waitcnt lgkmcnt(6)
	v_mfma_f32_32x32x16_bf16 v[32:47], v[72:75], v[116:119], v[32:47]
	ds_read_b64_tr_b16 v[116:117], v178 offset:0x3200
	ds_read_b64_tr_b16 v[118:119], v178 offset:0x3a00
	v_add_f32_e32 v222, v145, v222
	v_add_f32_e32 v222, v147, v222
	s_waitcnt lgkmcnt(6)
	v_mfma_f32_32x32x16_bf16 v[16:31], v[72:75], v[120:123], v[16:31]
	ds_read_b64_tr_b16 v[120:121], v178 offset:0x3400
	ds_read_b64_tr_b16 v[122:123], v178 offset:0x3c00
	v_add_f32_e32 v222, v149, v222
	v_add_f32_e32 v222, v151, v222
	s_waitcnt lgkmcnt(6)
	v_mfma_f32_32x32x16_bf16 v[0:15], v[72:75], v[124:127], v[0:15]
	ds_read_b64_tr_b16 v[124:125], v178 offset:0x3600
	ds_read_b64_tr_b16 v[126:127], v178 offset:0x3e00
	v_add_f32_e32 v222, v153, v222
	v_add_f32_e32 v222, v155, v222
	s_waitcnt lgkmcnt(6)
	v_mfma_f32_32x32x16_bf16 v[48:63], v[76:79], v[112:115], v[48:63]
	v_add_f32_e32 v222, v157, v222
	v_add_f32_e32 v222, v159, v222
	s_waitcnt lgkmcnt(4)
	v_mfma_f32_32x32x16_bf16 v[32:47], v[76:79], v[116:119], v[32:47]
	v_add_f32_e32 v222, v196, v222
	v_add_f32_e32 v222, v197, v222
	s_waitcnt lgkmcnt(2)
	v_mfma_f32_32x32x16_bf16 v[16:31], v[76:79], v[120:123], v[16:31]
	v_add_f32_e32 v222, v198, v222
	v_add_f32_e32 v222, v199, v222
	s_waitcnt lgkmcnt(0)
	v_mfma_f32_32x32x16_bf16 v[0:15], v[76:79], v[124:127], v[0:15]
	v_add_f32_e32 v222, v200, v222
	v_add_f32_e32 v222, v201, v222
	v_add_f32_e32 v222, v128, v222
	s_setprio 0
	s_mul_i32 s58, s54, 0x3800
	s_mul_hi_u32 s59, s54, 0x3800
	s_add_u32 s58, s18, s58
	s_addc_u32 s59, s19, s59
	s_add_i32 vcc_lo, s53, 0xffffc000
	s_and_b32 s60, vcc_lo, 0xc000
	s_add_i32 s61, s25, s60
	s_add_u32 vcc_lo, s58, 0x70000
	s_mov_b32 m0, s61
	s_addc_u32 vcc_hi, s59, 0
	s_waitcnt vmcnt(0)
	s_waitcnt vmcnt(0)
	s_barrier
; __device__ __forceinline__ void bias_init(f32x16& p0, f32x16& p1, float base, float nslope2, float nM2, int rel  ) {
;     if (rel <= -63 || rel >= 31) {
;         const float sg = (rel < 0) ? -nslope2 : nslope2, lbv = fmaf(-sg, base, nM2);
; #pragma unroll
;         for (int r = 0; r < 16; ++r) { p0[r] = fmaf((float)((r & 3) + 8 * (r >> 2)), sg, lbv); p1[r] = fmaf((float)((r & 3) + 8 * (r >> 2) + 32), sg, lbv); }
	global_load_lds_dwordx4 v176, s[58:59]
	s_add_i32 m0, s61, 0x2000
	s_nop 0
	global_load_lds_dwordx4 v176, vcc
	s_add_i32 s100, s24, s60
	s_mov_b32 m0, s100
	s_nop 0
	global_load_lds_dwordx4 v188, s[58:59]
	s_add_i32 m0, s100, 0x2000
	s_nop 0
	global_load_lds_dwordx4 v188, vcc
	v_subrev_u32_e32 v64, 64, v139
	v_cvt_f32_i32_e32 v194, v64
	s_add_i32 s58, s57, 0xffffffa1
	s_cmp_lt_u32 s58, 0xffffffa3
	s_mov_b64 vcc, -1
	s_cbranch_scc1 .LBB0_254
	s_mov_b32 s58, -2.0
	v_add_f32_e32 v195, -1.0, v194
	s_mov_b32 s59, 0xc0400000
	v_pk_add_f32 v[112:113], v[194:195], s[58:59] op_sel_hi:[0,1]
	s_mov_b32 s58, 0xc1000000
	s_mov_b32 s59, 0xc1100000
	v_pk_add_f32 v[114:115], v[194:195], s[58:59] op_sel_hi:[0,1]
	s_mov_b32 s58, 0xc1200000
	s_mov_b32 s59, 0xc1300000
	v_pk_add_f32 v[116:117], v[194:195], s[58:59] op_sel_hi:[0,1]
	s_mov_b32 s58, 0xc1800000
	s_mov_b32 s59, 0xc1880000
	v_pk_add_f32 v[118:119], v[194:195], s[58:59] op_sel_hi:[0,1]
	s_mov_b32 s58, 0xc1900000
	s_mov_b32 s59, 0xc1980000
	v_pk_add_f32 v[120:121], v[194:195], s[58:59] op_sel_hi:[0,1]
	s_mov_b32 s58, 0xc1c00000
	s_mov_b32 s59, 0xc1c80000
	v_pk_add_f32 v[122:123], v[194:195], s[58:59] op_sel_hi:[0,1]
	s_mov_b32 s58, 0xc1d00000
	s_mov_b32 s59, 0xc1d80000
	v_pk_add_f32 v[64:65], v[194:195], s[26:27] op_sel_hi:[1,0]
	v_pk_add_f32 v[66:67], v[112:113], s[26:27] op_sel_hi:[1,0]
	v_pk_add_f32 v[68:69], v[114:115], s[26:27] op_sel_hi:[1,0]
	v_pk_add_f32 v[70:71], v[116:117], s[26:27] op_sel_hi:[1,0]
	v_pk_add_f32 v[72:73], v[118:119], s[26:27] op_sel_hi:[1,0]
	v_pk_add_f32 v[74:75], v[120:121], s[26:27] op_sel_hi:[1,0]
	v_pk_add_f32 v[76:77], v[122:123], s[26:27] op_sel_hi:[1,0]
	v_pk_add_f32 v[178:179], v[194:195], s[58:59] op_sel_hi:[0,1]
	v_and_b32_e32 v65, 0x7fffffff, v65
	v_and_b32_e32 v64, 0x7fffffff, v64
	v_and_b32_e32 v67, 0x7fffffff, v67
	v_and_b32_e32 v66, 0x7fffffff, v66
	v_and_b32_e32 v69, 0x7fffffff, v69
	v_and_b32_e32 v68, 0x7fffffff, v68
	v_and_b32_e32 v71, 0x7fffffff, v71
	v_and_b32_e32 v70, 0x7fffffff, v70
	v_and_b32_e32 v73, 0x7fffffff, v73
	v_and_b32_e32 v72, 0x7fffffff, v72
	v_and_b32_e32 v75, 0x7fffffff, v75
	v_and_b32_e32 v74, 0x7fffffff, v74
	v_and_b32_e32 v77, 0x7fffffff, v77
	v_and_b32_e32 v76, 0x7fffffff, v76
	v_add_f32_e32 v78, 0xc2000000, v178
	v_and_b32_e32 v113, 0x7fffffff, v113
	v_and_b32_e32 v112, 0x7fffffff, v112
	v_and_b32_e32 v115, 0x7fffffff, v115
	v_and_b32_e32 v114, 0x7fffffff, v114
	v_and_b32_e32 v117, 0x7fffffff, v117
	v_and_b32_e32 v116, 0x7fffffff, v116
	v_and_b32_e32 v119, 0x7fffffff, v119
	v_and_b32_e32 v118, 0x7fffffff, v118
	v_and_b32_e32 v121, 0x7fffffff, v121
	v_and_b32_e32 v120, 0x7fffffff, v120
	v_and_b32_e32 v123, 0x7fffffff, v123
	v_and_b32_e32 v122, 0x7fffffff, v122
	v_and_b32_e32 v125, 0x7fffffff, v179
	v_and_b32_e32 v124, 0x7fffffff, v178
	v_and_b32_e32 v180, 0x7fffffff, v194
	v_and_b32_e32 v181, 0x7fffffff, v195
	v_mov_b32_e32 v187, v186
	v_add_f32_e32 v79, 0xc2000000, v179
	v_pk_fma_f32 v[64:65], v[64:65], v[190:191], s[16:17]
	v_pk_fma_f32 v[66:67], v[66:67], v[190:191], s[16:17]
	v_pk_fma_f32 v[68:69], v[68:69], v[190:191], s[16:17]
	v_pk_fma_f32 v[70:71], v[70:71], v[190:191], s[16:17]
	v_pk_fma_f32 v[72:73], v[72:73], v[190:191], s[16:17]
	v_pk_fma_f32 v[74:75], v[74:75], v[190:191], s[16:17]
	v_pk_fma_f32 v[76:77], v[76:77], v[190:191], s[16:17]
	v_fma_f32 v78, |v78|, v186, s16
	v_pk_fma_f32 v[126:127], v[124:125], v[186:187], s[50:51]
	v_pk_fma_f32 v[124:125], v[122:123], v[186:187], s[48:49]
	v_pk_fma_f32 v[122:123], v[120:121], v[186:187], s[46:47]
	v_pk_fma_f32 v[120:121], v[118:119], v[186:187], s[44:45]
	v_pk_fma_f32 v[118:119], v[116:117], v[186:187], s[34:35]
	v_pk_fma_f32 v[116:117], v[114:115], v[186:187], s[20:21]
	v_pk_fma_f32 v[114:115], v[112:113], v[186:187], s[8:9]
	v_pk_fma_f32 v[112:113], v[180:181], v[192:193], s[6:7]
	v_fma_f32 v79, |v79|, v186, s16
	s_mov_b64 vcc, 0
